# opt20: opt19 + G8 EpiFinal phase A: residual loads of row groups 1,3,5,7 issued one group early into spare VGPRs (saddr), waits recounted
# baseline (speedup 1.0000x reference)
;     __device__ __forceinline__ void operator()(Acc& acc, const Unit& u, int wr, int wc, int fr, int fq) const {
;     ...
;                 const int rt = rt0 + ai * HALF + m * 16; float sq = 0.f;
; #pragma unroll
;                 for (int bj = 0; bj < 2; ++bj) {
;                     const size_t off = (size_t)(u.pm * BM + rt) * DM + col0 + bj * HALF;
;                     const f32x4 b0 = *(const f32x4*)(base + off), b1 = *(const f32x4*)(base + off + 4);
;                     const f32x4 x0 = b0 + acc[ai][bj][m][0] * alpha, x1 = b1 + acc[ai][bj][m][1] * alpha;
;                     acc[ai][bj][m][0] = x0; acc[ai][bj][m][1] = x1;
;                     sq += (x0[0] * x0[0] + x0[1] * x0[1]) + (x0[2] * x0[2] + x0[3] * x0[3]) + (x1[0] * x1[0] + x1[1] * x1[1]) + (x1[2] * x1[2] + x1[3] * x1[3]);
;                 }
;                 sq += __shfl_xor(sq, 16); sq += __shfl_xor(sq, 32);
;                 if (fq == 0) P[rt * 4 + wc] = sq;
.LBB0_1436:
	s_lshl_b32 s25, s49, 8
	v_add_u32_e32 v144, s25, v183
	v_ashrrev_i32_e32 v145, 31, v144
	v_lshl_or_b32 v154, s24, 8, v185
	v_lshlrev_b64 v[144:145], 12, v[144:145]
	v_ashrrev_i32_e32 v155, 31, v154
	v_lshl_add_u64 v[144:145], s[82:83], 0, v[144:145]
	v_lshl_add_u64 v[144:145], v[154:155], 2, v[144:145]
	global_load_dwordx4 v[146:149], v[144:145], off
	global_load_dwordx4 v[150:153], v[144:145], off offset:16
	global_load_dwordx4 v[156:159], v[144:145], off offset:512
	global_load_dwordx4 v[160:163], v[144:145], off offset:528
	v_add_u32_e32 v244, s25, v186
	v_lshlrev_b32_e32 v244, 12, v244
	v_lshl_add_u32 v244, v154, 2, v244
	global_load_dwordx4 v[228:231], v244, s[82:83]
	global_load_dwordx4 v[232:235], v244, s[82:83] offset:16
	global_load_dwordx4 v[236:239], v244, s[82:83] offset:512
	global_load_dwordx4 v[240:243], v244, s[82:83] offset:528
	s_waitcnt vmcnt(4)
	v_pk_fma_f32 v[126:127], v[126:127], 0.5, v[148:149] op_sel_hi:[1,0,1]
	v_pk_fma_f32 v[124:125], v[124:125], 0.5, v[146:147] op_sel_hi:[1,0,1]
	v_pk_fma_f32 v[118:119], v[118:119], 0.5, v[158:159] op_sel_hi:[1,0,1]
	v_pk_fma_f32 v[116:117], v[116:117], 0.5, v[156:157] op_sel_hi:[1,0,1]
	v_pk_fma_f32 v[120:121], v[120:121], 0.5, v[150:151] op_sel_hi:[1,0,1]
	v_pk_fma_f32 v[146:147], v[112:113], 0.5, v[160:161] op_sel_hi:[1,0,1]
	v_mul_f32_e32 v112, v125, v125
	v_mul_f32_e32 v113, v127, v127
	v_mul_f32_e32 v150, v117, v117
	v_mul_f32_e32 v151, v119, v119
	v_pk_fma_f32 v[122:123], v[122:123], 0.5, v[152:153] op_sel_hi:[1,0,1]
	v_pk_fma_f32 v[114:115], v[114:115], 0.5, v[162:163] op_sel_hi:[1,0,1]
	v_mul_f32_e32 v148, v121, v121
	v_mul_f32_e32 v152, v147, v147
	v_fmac_f32_e32 v112, v124, v124
	v_fmac_f32_e32 v113, v126, v126
	v_fmac_f32_e32 v150, v116, v116
	v_fmac_f32_e32 v151, v118, v118
	v_mul_f32_e32 v149, v123, v123
	v_mul_f32_e32 v153, v115, v115
	v_fmac_f32_e32 v148, v120, v120
	v_fmac_f32_e32 v152, v146, v146
	v_add_f32_e32 v112, v112, v113
	v_add_f32_e32 v113, v150, v151
	v_fmac_f32_e32 v149, v122, v122
	v_fmac_f32_e32 v153, v114, v114
	v_add_f32_e32 v112, v148, v112
	v_add_f32_e32 v113, v152, v113
	v_add_f32_e32 v112, v149, v112
	v_add_f32_e32 v113, v153, v113
	v_add_f32_e32 v112, v112, v113
	ds_bpermute_b32 v113, v181, v112
	s_waitcnt lgkmcnt(0)
	v_add_f32_e32 v112, v112, v113
	ds_bpermute_b32 v113, v182, v112
	s_and_saveexec_b64 s[26:27], s[2:3]
	s_cbranch_execz .LBB0_1438
	s_waitcnt lgkmcnt(0)
	v_add_f32_e32 v112, v112, v113
	ds_write_b32 v205, v112
.LBB0_1438:
	s_or_b64 exec, exec, s[26:27]
	v_add_u32_e32 v112, s25, v186
	s_waitcnt lgkmcnt(0)
	v_ashrrev_i32_e32 v113, 31, v112
	v_lshlrev_b64 v[112:113], 12, v[112:113]
	v_lshl_add_u64 v[112:113], s[82:83], 0, v[112:113]
	v_lshl_add_u64 v[112:113], v[154:155], 2, v[112:113]
	s_waitcnt vmcnt(3)
	v_pk_fma_f32 v[110:111], v[110:111], 0.5, v[230:231] op_sel_hi:[1,0,1]
	v_pk_fma_f32 v[108:109], v[108:109], 0.5, v[228:229] op_sel_hi:[1,0,1]
	s_waitcnt vmcnt(1)
	v_pk_fma_f32 v[102:103], v[102:103], 0.5, v[238:239] op_sel_hi:[1,0,1]
	v_pk_fma_f32 v[100:101], v[100:101], 0.5, v[236:237] op_sel_hi:[1,0,1]
	v_pk_fma_f32 v[104:105], v[104:105], 0.5, v[232:233] op_sel_hi:[1,0,1]
	s_waitcnt vmcnt(0)
	v_pk_fma_f32 v[96:97], v[96:97], 0.5, v[240:241] op_sel_hi:[1,0,1]
	v_mul_f32_e32 v148, v109, v109
	v_mul_f32_e32 v149, v111, v111
	v_mul_f32_e32 v152, v101, v101
	v_mul_f32_e32 v153, v103, v103
	v_pk_fma_f32 v[106:107], v[106:107], 0.5, v[234:235] op_sel_hi:[1,0,1]
	v_pk_fma_f32 v[98:99], v[98:99], 0.5, v[242:243] op_sel_hi:[1,0,1]
	v_mul_f32_e32 v150, v105, v105
	v_mul_f32_e32 v156, v97, v97
	v_fmac_f32_e32 v148, v108, v108
	v_fmac_f32_e32 v149, v110, v110
	v_fmac_f32_e32 v152, v100, v100
	v_fmac_f32_e32 v153, v102, v102
	v_mul_f32_e32 v151, v107, v107
	v_mul_f32_e32 v157, v99, v99
	v_fmac_f32_e32 v150, v104, v104
	v_fmac_f32_e32 v156, v96, v96
	v_add_f32_e32 v148, v148, v149
	v_add_f32_e32 v149, v152, v153
	v_fmac_f32_e32 v151, v106, v106
	v_fmac_f32_e32 v157, v98, v98
	v_add_f32_e32 v148, v150, v148
	v_add_f32_e32 v149, v156, v149
	v_add_f32_e32 v148, v151, v148
	v_add_f32_e32 v149, v157, v149
	v_add_f32_e32 v148, v148, v149
	ds_bpermute_b32 v149, v181, v148
	s_waitcnt lgkmcnt(0)
	v_add_f32_e32 v148, v148, v149
	ds_bpermute_b32 v149, v182, v148
	s_mov_b64 s[26:27], exec
	s_and_b64 s[34:35], s[26:27], s[2:3]
	v_mov_b32_e32 v246, v180
	s_mov_b64 exec, s[34:35]
	s_cbranch_execz .LBB0_1440
	s_waitcnt lgkmcnt(0)
	v_add_f32_e32 v148, v148, v149
	ds_write_b32 v206, v148
;     __device__ __forceinline__ void operator()(Acc& acc, const Unit& u, int wr, int wc, int fr, int fq) const {
;     ...
;                 const int rt = rt0 + ai * HALF + m * 16; float sq = 0.f;
; #pragma unroll
;                 for (int bj = 0; bj < 2; ++bj) {
;                     const size_t off = (size_t)(u.pm * BM + rt) * DM + col0 + bj * HALF;
;                     const f32x4 b0 = *(const f32x4*)(base + off), b1 = *(const f32x4*)(base + off + 4);
;                     const f32x4 x0 = b0 + acc[ai][bj][m][0] * alpha, x1 = b1 + acc[ai][bj][m][1] * alpha;
;                     acc[ai][bj][m][0] = x0; acc[ai][bj][m][1] = x1;
;                     sq += (x0[0] * x0[0] + x0[1] * x0[1]) + (x0[2] * x0[2] + x0[3] * x0[3]) + (x1[0] * x1[0] + x1[1] * x1[1]) + (x1[2] * x1[2] + x1[3] * x1[3]);
;                 }
;                 sq += __shfl_xor(sq, 16); sq += __shfl_xor(sq, 32);
;                 if (fq == 0) P[rt * 4 + wc] = sq;
.LBB0_1440:
	s_or_b64 exec, exec, s[26:27]
	v_add_u32_e32 v148, s25, v187
	s_waitcnt lgkmcnt(0)
	v_ashrrev_i32_e32 v149, 31, v148
	v_lshlrev_b64 v[148:149], 12, v[148:149]
	v_lshl_add_u64 v[148:149], s[82:83], 0, v[148:149]
	v_lshl_add_u64 v[148:149], v[154:155], 2, v[148:149]
	global_load_dwordx4 v[150:153], v[148:149], off
	global_load_dwordx4 v[156:159], v[148:149], off offset:16
	global_load_dwordx4 v[160:163], v[148:149], off offset:512
	global_load_dwordx4 v[164:167], v[148:149], off offset:528
	v_add_u32_e32 v244, s25, v188
	v_lshlrev_b32_e32 v244, 12, v244
	v_lshl_add_u32 v244, v154, 2, v244
	global_load_dwordx4 v[228:231], v244, s[82:83]
	global_load_dwordx4 v[232:235], v244, s[82:83] offset:16
	global_load_dwordx4 v[236:239], v244, s[82:83] offset:512
	global_load_dwordx4 v[240:243], v244, s[82:83] offset:528
	s_waitcnt vmcnt(7)
	v_pk_fma_f32 v[94:95], v[94:95], 0.5, v[152:153] op_sel_hi:[1,0,1]
	v_pk_fma_f32 v[92:93], v[92:93], 0.5, v[150:151] op_sel_hi:[1,0,1]
	s_waitcnt vmcnt(5)
	v_pk_fma_f32 v[86:87], v[86:87], 0.5, v[162:163] op_sel_hi:[1,0,1]
	v_pk_fma_f32 v[84:85], v[84:85], 0.5, v[160:161] op_sel_hi:[1,0,1]
	v_pk_fma_f32 v[88:89], v[88:89], 0.5, v[156:157] op_sel_hi:[1,0,1]
	s_waitcnt vmcnt(4)
	v_pk_fma_f32 v[150:151], v[80:81], 0.5, v[164:165] op_sel_hi:[1,0,1]
	v_mul_f32_e32 v80, v93, v93
	v_mul_f32_e32 v81, v95, v95
	v_mul_f32_e32 v156, v85, v85
	v_mul_f32_e32 v157, v87, v87
	v_pk_fma_f32 v[90:91], v[90:91], 0.5, v[158:159] op_sel_hi:[1,0,1]
	v_pk_fma_f32 v[82:83], v[82:83], 0.5, v[166:167] op_sel_hi:[1,0,1]
	v_mul_f32_e32 v152, v89, v89
	v_mul_f32_e32 v158, v151, v151
	v_fmac_f32_e32 v80, v92, v92
	v_fmac_f32_e32 v81, v94, v94
	v_fmac_f32_e32 v156, v84, v84
	v_fmac_f32_e32 v157, v86, v86
	v_mul_f32_e32 v153, v91, v91
	v_mul_f32_e32 v159, v83, v83
	v_fmac_f32_e32 v152, v88, v88
	v_fmac_f32_e32 v158, v150, v150
	v_add_f32_e32 v80, v80, v81
	v_add_f32_e32 v81, v156, v157
	v_fmac_f32_e32 v153, v90, v90
	v_fmac_f32_e32 v159, v82, v82
	v_add_f32_e32 v80, v152, v80
	v_add_f32_e32 v81, v158, v81
	v_add_f32_e32 v80, v153, v80
	v_add_f32_e32 v81, v159, v81
	v_add_f32_e32 v80, v80, v81
	ds_bpermute_b32 v81, v181, v80
	s_waitcnt lgkmcnt(0)
	v_add_f32_e32 v80, v80, v81
	ds_bpermute_b32 v81, v182, v80
	s_and_saveexec_b64 s[26:27], s[2:3]
	s_cbranch_execz .LBB0_1442
	s_waitcnt lgkmcnt(0)
	v_add_f32_e32 v80, v80, v81
	ds_write_b32 v207, v80
.LBB0_1442:
	s_or_b64 exec, exec, s[26:27]
	v_add_u32_e32 v80, s25, v188
	s_waitcnt lgkmcnt(0)
	v_ashrrev_i32_e32 v81, 31, v80
	v_lshlrev_b64 v[80:81], 12, v[80:81]
	v_lshl_add_u64 v[80:81], s[82:83], 0, v[80:81]
	v_lshl_add_u64 v[80:81], v[154:155], 2, v[80:81]
	s_waitcnt vmcnt(3)
	v_pk_fma_f32 v[78:79], v[78:79], 0.5, v[230:231] op_sel_hi:[1,0,1]
	v_pk_fma_f32 v[152:153], v[76:77], 0.5, v[228:229] op_sel_hi:[1,0,1]
	s_waitcnt vmcnt(1)
	v_pk_fma_f32 v[70:71], v[70:71], 0.5, v[238:239] op_sel_hi:[1,0,1]
	v_pk_fma_f32 v[68:69], v[68:69], 0.5, v[236:237] op_sel_hi:[1,0,1]
	v_pk_fma_f32 v[76:77], v[72:73], 0.5, v[232:233] op_sel_hi:[1,0,1]
	s_waitcnt vmcnt(0)
	v_pk_fma_f32 v[64:65], v[64:65], 0.5, v[240:241] op_sel_hi:[1,0,1]
	v_mul_f32_e32 v72, v153, v153
	v_mul_f32_e32 v73, v79, v79
	v_mul_f32_e32 v158, v69, v69
	v_mul_f32_e32 v159, v71, v71
	v_pk_fma_f32 v[74:75], v[74:75], 0.5, v[234:235] op_sel_hi:[1,0,1]
	v_pk_fma_f32 v[66:67], v[66:67], 0.5, v[242:243] op_sel_hi:[1,0,1]
	v_mul_f32_e32 v156, v77, v77
	v_mul_f32_e32 v160, v65, v65
	v_fmac_f32_e32 v72, v152, v152
	v_fmac_f32_e32 v73, v78, v78
	v_fmac_f32_e32 v158, v68, v68
	v_fmac_f32_e32 v159, v70, v70
	v_mul_f32_e32 v157, v75, v75
	v_mul_f32_e32 v161, v67, v67
	v_fmac_f32_e32 v156, v76, v76
	v_fmac_f32_e32 v160, v64, v64
	v_add_f32_e32 v72, v72, v73
	v_add_f32_e32 v73, v158, v159
	v_fmac_f32_e32 v157, v74, v74
	v_fmac_f32_e32 v161, v66, v66
	v_add_f32_e32 v72, v156, v72
	v_add_f32_e32 v73, v160, v73
	v_add_f32_e32 v72, v157, v72
	v_add_f32_e32 v73, v161, v73
	v_add_f32_e32 v72, v72, v73
	ds_bpermute_b32 v73, v181, v72
	s_waitcnt lgkmcnt(0)
	v_add_f32_e32 v72, v72, v73
	ds_bpermute_b32 v73, v182, v72
	s_and_saveexec_b64 s[26:27], s[2:3]
	s_cbranch_execz .LBB0_1444
	s_waitcnt lgkmcnt(0)
	v_add_f32_e32 v72, v72, v73
	ds_write_b32 v208, v72
.LBB0_1444:
	s_or_b64 exec, exec, s[26:27]
	v_add_u32_e32 v72, s25, v189
	s_waitcnt lgkmcnt(0)
	v_ashrrev_i32_e32 v73, 31, v72
	v_lshlrev_b64 v[72:73], 12, v[72:73]
	v_lshl_add_u64 v[72:73], s[82:83], 0, v[72:73]
	v_lshl_add_u64 v[72:73], v[154:155], 2, v[72:73]
	global_load_dwordx4 v[156:159], v[72:73], off
	global_load_dwordx4 v[160:163], v[72:73], off offset:16
	global_load_dwordx4 v[164:167], v[72:73], off offset:512
	global_load_dwordx4 v[168:171], v[72:73], off offset:528
	v_add_u32_e32 v244, s25, v190
	v_lshlrev_b32_e32 v244, 12, v244
	v_lshl_add_u32 v244, v154, 2, v244
	global_load_dwordx4 v[228:231], v244, s[82:83]
	global_load_dwordx4 v[232:235], v244, s[82:83] offset:16
	global_load_dwordx4 v[236:239], v244, s[82:83] offset:512
	global_load_dwordx4 v[240:243], v244, s[82:83] offset:528
	s_waitcnt vmcnt(7)
	v_pk_fma_f32 v[62:63], v[62:63], 0.5, v[158:159] op_sel_hi:[1,0,1]
	v_pk_fma_f32 v[60:61], v[60:61], 0.5, v[156:157] op_sel_hi:[1,0,1]
	s_waitcnt vmcnt(5)
	v_pk_fma_f32 v[54:55], v[54:55], 0.5, v[166:167] op_sel_hi:[1,0,1]
	v_pk_fma_f32 v[52:53], v[52:53], 0.5, v[164:165] op_sel_hi:[1,0,1]
	v_pk_fma_f32 v[56:57], v[56:57], 0.5, v[160:161] op_sel_hi:[1,0,1]
	s_waitcnt vmcnt(4)
	v_pk_fma_f32 v[48:49], v[48:49], 0.5, v[168:169] op_sel_hi:[1,0,1]
	v_mul_f32_e32 v156, v61, v61
	v_mul_f32_e32 v157, v63, v63
	v_mul_f32_e32 v160, v53, v53
	v_mul_f32_e32 v161, v55, v55
	v_pk_fma_f32 v[58:59], v[58:59], 0.5, v[162:163] op_sel_hi:[1,0,1]
	v_pk_fma_f32 v[50:51], v[50:51], 0.5, v[170:171] op_sel_hi:[1,0,1]
	v_mul_f32_e32 v158, v57, v57
	v_mul_f32_e32 v162, v49, v49
	v_fmac_f32_e32 v156, v60, v60
	v_fmac_f32_e32 v157, v62, v62
	v_fmac_f32_e32 v160, v52, v52
	v_fmac_f32_e32 v161, v54, v54
	v_mul_f32_e32 v159, v59, v59
	v_mul_f32_e32 v163, v51, v51
	v_fmac_f32_e32 v158, v56, v56
	v_fmac_f32_e32 v162, v48, v48
	v_add_f32_e32 v156, v156, v157
	v_add_f32_e32 v157, v160, v161
	v_fmac_f32_e32 v159, v58, v58
	v_fmac_f32_e32 v163, v50, v50
	v_add_f32_e32 v156, v158, v156
	v_add_f32_e32 v157, v162, v157
	v_add_f32_e32 v156, v159, v156
	v_add_f32_e32 v157, v163, v157
	v_add_f32_e32 v156, v156, v157
	ds_bpermute_b32 v157, v181, v156
	s_waitcnt lgkmcnt(0)
	v_add_f32_e32 v156, v156, v157
	ds_bpermute_b32 v157, v182, v156
	s_and_saveexec_b64 s[26:27], s[2:3]
	s_cbranch_execz .LBB0_1446
	s_waitcnt lgkmcnt(0)
	v_add_f32_e32 v156, v156, v157
	ds_write_b32 v209, v156
;     __device__ __forceinline__ void operator()(Acc& acc, const Unit& u, int wr, int wc, int fr, int fq) const {
;     ...
;                 const int rt = rt0 + ai * HALF + m * 16; float sq = 0.f;
; #pragma unroll
;                 for (int bj = 0; bj < 2; ++bj) {
;                     const size_t off = (size_t)(u.pm * BM + rt) * DM + col0 + bj * HALF;
;                     const f32x4 b0 = *(const f32x4*)(base + off), b1 = *(const f32x4*)(base + off + 4);
;                     const f32x4 x0 = b0 + acc[ai][bj][m][0] * alpha, x1 = b1 + acc[ai][bj][m][1] * alpha;
;                     acc[ai][bj][m][0] = x0; acc[ai][bj][m][1] = x1;
;                     sq += (x0[0] * x0[0] + x0[1] * x0[1]) + (x0[2] * x0[2] + x0[3] * x0[3]) + (x1[0] * x1[0] + x1[1] * x1[1]) + (x1[2] * x1[2] + x1[3] * x1[3]);
;                 }
;                 sq += __shfl_xor(sq, 16); sq += __shfl_xor(sq, 32);
;                 if (fq == 0) P[rt * 4 + wc] = sq;
.LBB0_1446:
	s_or_b64 exec, exec, s[26:27]
	v_add_u32_e32 v156, s25, v190
	s_waitcnt lgkmcnt(0)
	v_ashrrev_i32_e32 v157, 31, v156
	v_lshlrev_b64 v[156:157], 12, v[156:157]
	v_lshl_add_u64 v[156:157], s[82:83], 0, v[156:157]
	v_lshl_add_u64 v[156:157], v[154:155], 2, v[156:157]
	s_waitcnt vmcnt(3)
	v_pk_fma_f32 v[46:47], v[46:47], 0.5, v[230:231] op_sel_hi:[1,0,1]
	v_pk_fma_f32 v[44:45], v[44:45], 0.5, v[228:229] op_sel_hi:[1,0,1]
	s_waitcnt vmcnt(1)
	v_pk_fma_f32 v[38:39], v[38:39], 0.5, v[238:239] op_sel_hi:[1,0,1]
	v_pk_fma_f32 v[36:37], v[36:37], 0.5, v[236:237] op_sel_hi:[1,0,1]
	v_pk_fma_f32 v[40:41], v[40:41], 0.5, v[232:233] op_sel_hi:[1,0,1]
	s_waitcnt vmcnt(0)
	v_pk_fma_f32 v[32:33], v[32:33], 0.5, v[240:241] op_sel_hi:[1,0,1]
	v_mul_f32_e32 v158, v45, v45
	v_mul_f32_e32 v159, v47, v47
	v_mul_f32_e32 v162, v37, v37
	v_mul_f32_e32 v163, v39, v39
	v_pk_fma_f32 v[42:43], v[42:43], 0.5, v[234:235] op_sel_hi:[1,0,1]
	v_pk_fma_f32 v[34:35], v[34:35], 0.5, v[242:243] op_sel_hi:[1,0,1]
	v_mul_f32_e32 v160, v41, v41
	v_mul_f32_e32 v164, v33, v33
	v_fmac_f32_e32 v158, v44, v44
	v_fmac_f32_e32 v159, v46, v46
	v_fmac_f32_e32 v162, v36, v36
	v_fmac_f32_e32 v163, v38, v38
	v_mul_f32_e32 v161, v43, v43
	v_mul_f32_e32 v165, v35, v35
	v_fmac_f32_e32 v160, v40, v40
	v_fmac_f32_e32 v164, v32, v32
	v_add_f32_e32 v158, v158, v159
	v_add_f32_e32 v159, v162, v163
	v_fmac_f32_e32 v161, v42, v42
	v_fmac_f32_e32 v165, v34, v34
	v_add_f32_e32 v158, v160, v158
	v_add_f32_e32 v159, v164, v159
	v_add_f32_e32 v158, v161, v158
	v_add_f32_e32 v159, v165, v159
	v_add_f32_e32 v158, v158, v159
	ds_bpermute_b32 v159, v181, v158
	s_waitcnt lgkmcnt(0)
	v_add_f32_e32 v158, v158, v159
	ds_bpermute_b32 v159, v182, v158
	s_and_saveexec_b64 s[26:27], s[2:3]
	s_cbranch_execz .LBB0_1448
	s_waitcnt lgkmcnt(0)
	v_add_f32_e32 v158, v158, v159
	ds_write_b32 v210, v158
.LBB0_1448:
	s_or_b64 exec, exec, s[26:27]
	v_add_u32_e32 v158, s25, v191
	s_waitcnt lgkmcnt(0)
	v_ashrrev_i32_e32 v159, 31, v158
	v_lshlrev_b64 v[158:159], 12, v[158:159]
	v_lshl_add_u64 v[158:159], s[82:83], 0, v[158:159]
	v_lshl_add_u64 v[158:159], v[154:155], 2, v[158:159]
	global_load_dwordx4 v[160:163], v[158:159], off
	global_load_dwordx4 v[164:167], v[158:159], off offset:16
	global_load_dwordx4 v[168:171], v[158:159], off offset:512
	global_load_dwordx4 v[172:175], v[158:159], off offset:528
	v_add_u32_e32 v244, s25, v192
	v_lshlrev_b32_e32 v244, 12, v244
	v_lshl_add_u32 v244, v154, 2, v244
	global_load_dwordx4 v[228:231], v244, s[82:83]
	global_load_dwordx4 v[232:235], v244, s[82:83] offset:16
	global_load_dwordx4 v[236:239], v244, s[82:83] offset:512
	global_load_dwordx4 v[240:243], v244, s[82:83] offset:528
	s_waitcnt vmcnt(7)
	v_pk_fma_f32 v[30:31], v[30:31], 0.5, v[162:163] op_sel_hi:[1,0,1]
	v_pk_fma_f32 v[28:29], v[28:29], 0.5, v[160:161] op_sel_hi:[1,0,1]
	s_waitcnt vmcnt(5)
	v_pk_fma_f32 v[22:23], v[22:23], 0.5, v[170:171] op_sel_hi:[1,0,1]
	v_pk_fma_f32 v[20:21], v[20:21], 0.5, v[168:169] op_sel_hi:[1,0,1]
	v_pk_fma_f32 v[24:25], v[24:25], 0.5, v[164:165] op_sel_hi:[1,0,1]
	s_waitcnt vmcnt(4)
	v_pk_fma_f32 v[16:17], v[16:17], 0.5, v[172:173] op_sel_hi:[1,0,1]
	v_mul_f32_e32 v160, v29, v29
	v_mul_f32_e32 v161, v31, v31
	v_mul_f32_e32 v164, v21, v21
	v_mul_f32_e32 v165, v23, v23
	v_pk_fma_f32 v[26:27], v[26:27], 0.5, v[166:167] op_sel_hi:[1,0,1]
	v_pk_fma_f32 v[18:19], v[18:19], 0.5, v[174:175] op_sel_hi:[1,0,1]
	v_mul_f32_e32 v162, v25, v25
	v_mul_f32_e32 v166, v17, v17
	v_fmac_f32_e32 v160, v28, v28
	v_fmac_f32_e32 v161, v30, v30
	v_fmac_f32_e32 v164, v20, v20
	v_fmac_f32_e32 v165, v22, v22
	v_mul_f32_e32 v163, v27, v27
	v_mul_f32_e32 v167, v19, v19
	v_fmac_f32_e32 v162, v24, v24
	v_fmac_f32_e32 v166, v16, v16
	v_add_f32_e32 v160, v160, v161
	v_add_f32_e32 v161, v164, v165
	v_fmac_f32_e32 v163, v26, v26
	v_fmac_f32_e32 v167, v18, v18
	v_add_f32_e32 v160, v162, v160
	v_add_f32_e32 v161, v166, v161
	v_add_f32_e32 v160, v163, v160
	v_add_f32_e32 v161, v167, v161
	v_add_f32_e32 v160, v160, v161
	ds_bpermute_b32 v161, v181, v160
	s_waitcnt lgkmcnt(0)
	v_add_f32_e32 v160, v160, v161
	ds_bpermute_b32 v161, v182, v160
	s_and_saveexec_b64 s[26:27], s[2:3]
	s_cbranch_execz .LBB0_1450
	s_waitcnt lgkmcnt(0)
	v_add_f32_e32 v160, v160, v161
	ds_write_b32 v211, v160
.LBB0_1450:
	s_or_b64 exec, exec, s[26:27]
	v_add_u32_e32 v160, s25, v192
	s_waitcnt lgkmcnt(0)
	v_ashrrev_i32_e32 v161, 31, v160
	v_lshlrev_b64 v[160:161], 12, v[160:161]
	v_lshl_add_u64 v[160:161], s[82:83], 0, v[160:161]
	v_lshl_add_u64 v[160:161], v[154:155], 2, v[160:161]
	s_waitcnt vmcnt(3)
	v_pk_fma_f32 v[174:175], v[14:15], 0.5, v[230:231] op_sel_hi:[1,0,1]
	v_pk_fma_f32 v[176:177], v[12:13], 0.5, v[228:229] op_sel_hi:[1,0,1]
	s_waitcnt vmcnt(2)
	v_pk_fma_f32 v[170:171], v[10:11], 0.5, v[234:235] op_sel_hi:[1,0,1]
	v_pk_fma_f32 v[172:173], v[8:9], 0.5, v[232:233] op_sel_hi:[1,0,1]
	s_waitcnt vmcnt(1)
	v_pk_fma_f32 v[166:167], v[6:7], 0.5, v[238:239] op_sel_hi:[1,0,1]
	v_pk_fma_f32 v[168:169], v[4:5], 0.5, v[236:237] op_sel_hi:[1,0,1]
	s_waitcnt vmcnt(0)
	v_pk_fma_f32 v[164:165], v[0:1], 0.5, v[240:241] op_sel_hi:[1,0,1]
	v_mul_f32_e32 v0, v177, v177
	v_mul_f32_e32 v1, v175, v175
	v_mul_f32_e32 v4, v169, v169
	v_mul_f32_e32 v5, v167, v167
	v_pk_fma_f32 v[162:163], v[2:3], 0.5, v[242:243] op_sel_hi:[1,0,1]
	v_mul_f32_e32 v2, v173, v173
	v_mul_f32_e32 v6, v165, v165
	v_fmac_f32_e32 v0, v176, v176
	v_fmac_f32_e32 v1, v174, v174
	v_fmac_f32_e32 v4, v168, v168
	v_fmac_f32_e32 v5, v166, v166
	v_mul_f32_e32 v3, v171, v171
	v_mul_f32_e32 v7, v163, v163
	v_fmac_f32_e32 v2, v172, v172
	v_fmac_f32_e32 v6, v164, v164
	v_add_f32_e32 v0, v0, v1
	v_add_f32_e32 v1, v4, v5
	v_fmac_f32_e32 v3, v170, v170
	v_fmac_f32_e32 v7, v162, v162
	v_add_f32_e32 v0, v2, v0
	v_add_f32_e32 v1, v6, v1
	v_add_f32_e32 v0, v3, v0
	v_add_f32_e32 v1, v7, v1
	v_add_f32_e32 v0, v0, v1
	ds_bpermute_b32 v1, v181, v0
	s_waitcnt lgkmcnt(0)
	v_add_f32_e32 v0, v0, v1
	ds_bpermute_b32 v1, v182, v0
	s_and_saveexec_b64 s[26:27], s[2:3]
	s_cbranch_execz .LBB0_1452
	s_waitcnt lgkmcnt(0)
	v_add_f32_e32 v0, v0, v1
	ds_write_b32 v212, v0
